# v30 + G4 third tile round split in two K halves across block pairs (c, c+64) with a device flag ordering the two residual adds (layers 0-2)
# baseline (speedup 1.0000x reference)
;     __device__ bool next(int i, pg8::Unit& u) const { if (i != 0) return false; u.pm = pm; u.pn = pn; return true; }
;     __device__ bool next(int i, pg8::Unit& u) const { if (!S.next(i, u)) return false; u.pm = (u.pm >> 3) * 9 + 1 + (u.pm & 7); return true; }
;     __host__ __device__ bool next(int i, Unit& u) const {
;         const long L = (long)i * G + c; if (L >= nwg) return false;
;         int wgid = (int)L; { const int q = nwg / NXCD, r = nwg % NXCD, xcd = wgid % NXCD, off = wgid / NXCD; wgid = (xcd < r ? xcd * (q + 1) : r * (q + 1) + (xcd - r) * q) + off; }
;         const int nig = WGM * nN, gid = wgid / nig, fm = gid * WGM, gsz = (nM - fm) < WGM ? (nM - fm) : WGM;
;         u.pm = fm + ((wgid % nig) % gsz); u.pn = (wgid % nig) / gsz; return true;
;     }
.LBB0_1086:
	s_add_i32 s15, s15, 1
	s_mul_i32 s12, s15, s3
	s_mul_hi_u32 s13, s15, s60
	s_add_i32 s13, s13, s12
	s_mul_i32 s12, s15, s60
	s_add_u32 s40, s12, s2
	s_addc_u32 s41, s13, s61
	s_cmp_lg_u32 s15, 2
	s_cbranch_scc1 .Lks4_a
	s_cmp_lg_u32 s60, 0x100
	s_cbranch_scc1 .Lks4_a
	s_cmp_lt_u32 s2, 64
	s_cbranch_scc1 .Lks4_a
	s_cmp_gt_u32 s2, 127
	s_cbranch_scc1 .Lks4_a
	s_add_u32 s40, s2, 0x1c0
	s_mov_b32 s41, 0
.Lks4_a:
	v_mov_b64_e32 v[0:1], 0x240
	v_cmp_lt_i64_e64 s[42:43], s[40:41], v[0:1]
	v_mov_b64_e32 v[0:1], 0x23f
	v_cmp_gt_i64_e32 vcc, s[40:41], v[0:1]
	s_cbranch_vccnz .LBB0_1088
	s_ashr_i32 s12, s40, 31
	s_lshr_b32 s12, s12, 29
	s_add_i32 s12, s40, s12
	s_ashr_i32 s13, s12, 3
	s_and_b32 s12, s12, -8
	s_sub_i32 s12, s40, s12
	s_cmp_lt_i32 s12, 0
	s_movk_i32 s20, 0x49
	s_cselect_b32 s20, s20, 0x48
	s_mul_i32 s12, s12, s20
	s_add_i32 s12, s12, s13
	s_ashr_i32 s13, s12, 31
	s_lshr_b32 s13, s13, 28
	s_add_i32 s13, s12, s13
	s_ashr_i32 s20, s13, 4
	s_lshl_b32 s20, s20, 2
	s_sub_i32 s34, 0x90, s20
	s_min_i32 s34, s34, 4
	s_abs_i32 s35, s34
	v_cvt_f32_u32_e32 v0, s35
	s_sub_i32 s41, 0, s35
	s_and_b32 s13, s13, -16
	s_sub_i32 s12, s12, s13
	v_rcp_iflag_f32_e32 v0, v0
	s_abs_i32 s13, s12
	s_xor_b32 s40, s12, s34
	s_ashr_i32 s40, s40, 31
	v_mul_f32_e32 v0, 0x4f7ffffe, v0
	v_cvt_u32_f32_e32 v0, v0
	s_nop 0
	v_readfirstlane_b32 s46, v0
	s_mul_i32 s41, s41, s46
	s_mul_hi_u32 s41, s46, s41
	s_add_i32 s46, s46, s41
	s_mul_hi_u32 s41, s13, s46
	s_mul_i32 s46, s41, s35
	s_sub_i32 s13, s13, s46
	s_add_i32 s47, s41, 1
	s_sub_i32 s46, s13, s35
	s_cmp_ge_u32 s13, s35
	s_cselect_b32 s41, s47, s41
	s_cselect_b32 s13, s46, s13
	s_add_i32 s46, s41, 1
	s_cmp_ge_u32 s13, s35
	s_cselect_b32 s13, s46, s41
	s_xor_b32 s13, s13, s40
	s_sub_i32 s46, s13, s40
	s_mul_i32 s13, s46, s34
	s_sub_i32 s12, s12, s13
	s_add_i32 s47, s20, s12

;     __device__ bool next(int i, pg8::Unit& u) const { if (i != 0) return false; u.pm = pm; u.pn = pn; return true; }
;     __device__ bool next(int i, pg8::Unit& u) const { if (!S.next(i, u)) return false; u.pm = (u.pm >> 3) * 9 + 1 + (u.pm & 7); return true; }
; template <class Epi, class Sched, bool ALIGN_EPI = false, bool SP2 = false>
; __device__ __forceinline__ void gemm_phase(PG8_LAS unsigned char* lds, const Gemm g, const Sched& S, const Epi& E) {
;     ...
;         const bool has_next = S.next(ui + 1, nxt);
;         const char* nA = has_next ? (const char*)g.A + (size_t)nxt.pm * tstep : cA; const char* nB = has_next ? (const char*)g.Bt + (size_t)nxt.pn * tstep : cB;
;         for (int t = 0; t < nt; t += 2) {
;             const bool last = (t == nt - 2);
;             const char* a1 = cA + (size_t)(t + 1) * kstep;
;             const char* a2 = last ? nA : cA + (size_t)(t + 2) * kstep; const char* b2 = last ? nB : cB + (size_t)(t + 2) * kstep;
;             const char* a3 = a2 + kstep; const char* b3 = b2 + kstep;
;             if (last && has_next) S.a_ready(nxt);
.LBB0_1092:
	s_movk_i32 s100, 40
	s_movk_i32 s101, 41
	s_cmp_lg_u32 s60, 0x100
	s_cbranch_scc1 .Lks4_b
	s_cmp_eq_u32 s15, 3
	s_cselect_b32 s100, 18, s100
	s_cselect_b32 s101, 19, s101
	s_cmp_lg_u32 s15, 2
	s_cbranch_scc1 .Lks4_b
	s_cmp_lt_u32 s2, 64
	s_cbranch_scc1 .Lks4_b
	s_cmp_gt_u32 s2, 127
	s_cbranch_scc1 .Lks4_b
	s_add_u32 s42, s42, 0xb00
	s_addc_u32 s43, s43, 0
	s_add_u32 s48, s48, 0xb00
	s_addc_u32 s49, s49, 0

; #define PG8_STAGE(bufoff, gbase, voff) do { _Pragma("unroll") for (int _i = 0; _i < 2; ++_i) \
;         __builtin_amdgcn_global_load_lds((const unsigned*)((const char*)(gbase) + (voff)[_i]), (PG8_LAS unsigned*)(lds + (bufoff) + ldsw + _i * 8192), 16, 0, 0); } while (0)
; #define PG8_LDA(dst, b, h) do { _Pragma("unroll") for (int m = 0; m < 4; ++m) _Pragma("unroll") for (int k = 0; k < 2; ++k) dst[m][k] = *(const PG8_LAS bf16x8*)(lds + PG8_SA(b, h) + aoff + m * 2048 + k * 1024); } while (0)
; #define PG8_LDB(dst, b, h) do { _Pragma("unroll") for (int n = 0; n < 2; ++n) _Pragma("unroll") for (int k = 0; k < 2; ++k) dst[n][k] = *(const PG8_LAS bf16x8*)(lds + PG8_SB(b, h) + boff + n * 2048 + k * 1024); } while (0)
; #define PG8_MMA(ai, bj, At, Bt) do { __builtin_amdgcn_s_setprio(1); _Pragma("unroll") for (int m = 0; m < 4; ++m) _Pragma("unroll") for (int n = 0; n < 2; ++n) _Pragma("unroll") for (int k = 0; k < 2; ++k) \
;         acc[ai][bj][m][n] = __builtin_amdgcn_mfma_f32_16x16x32_bf16(Bt[n][k], At[m][k], acc[ai][bj][m][n], 0, 0, 0); __builtin_amdgcn_s_setprio(0); } while (0)
; #define PG8_WAIT_V(n) asm volatile("s_waitcnt vmcnt(" #n ")" ::: "memory")
; #define PG8_BAR __builtin_amdgcn_s_barrier()
; template <class Epi, class Sched, bool ALIGN_EPI = false, bool SP2 = false>
; __device__ __forceinline__ void gemm_phase(PG8_LAS unsigned char* lds, const Gemm g, const Sched& S, const Epi& E) {
;     ...
;         for (int t = 0; t < nt; t += 2) {
;             const bool last = (t == nt - 2);
;             const char* a1 = cA + (size_t)(t + 1) * kstep;
;             const char* a2 = last ? nA : cA + (size_t)(t + 2) * kstep; const char* b2 = last ? nB : cB + (size_t)(t + 2) * kstep;
;             const char* a3 = a2 + kstep; const char* b3 = b2 + kstep;
;             if (last && has_next) S.a_ready(nxt);
;             if constexpr (SP2) {
;             PG8_LDB(B0, 0, 0); PG8_LDB(B1, 0, 1); PG8_SCHED; PG8_LDA(At, 0, 0); PG8_STAGE(PG8_SA(1, 1), a1 + hstep, voffA);
;             PG8_WAIT_V(8); PG8_WAIT_L(0); PG8_BAR; PG8_MMA(0, 0, At, B0); PG8_MMA(0, 1, At, B1); PG8_BAR; PG8_SCHED;
;             PG8_LDA(At, 0, 1); PG8_STAGE(PG8_SB(0, 0), b2, voffB); PG8_STAGE(PG8_SB(0, 1), b2 + hstep, voffB); PG8_STAGE(PG8_SA(0, 0), a2, voffA);
;             PG8_WAIT_V(8); PG8_WAIT_L(0); PG8_BAR; PG8_MMA(1, 0, At, B0); PG8_MMA(1, 1, At, B1); PG8_BAR; PG8_SCHED;
.LBB0_1093:
	s_add_u32 s56, s50, 0x100
	s_addc_u32 s57, s51, 0
	s_add_i32 s20, 0, 0x10000
	s_cmp_eq_u32 s34, s100
	s_cselect_b32 vcc_hi, s43, s57
	s_cselect_b32 vcc_lo, s42, s56
	s_cselect_b32 s59, s49, s13
	s_cselect_b32 s58, s48, s12
	s_add_i32 s35, 0, 0x14000
	v_add_u32_e32 v108, s20, v170
	v_add_u32_e32 v168, s35, v170
	ds_read_b128 v[88:91], v108
	ds_read_b128 v[100:103], v108 offset:1024
	ds_read_b128 v[104:107], v108 offset:2048
	ds_read_b128 v[108:111], v108 offset:3072
	ds_read_b128 v[174:177], v168
	ds_read_b128 v[178:181], v168 offset:1024
	ds_read_b128 v[182:185], v168 offset:2048
	ds_read_b128 v[186:189], v168 offset:3072
	v_lshl_add_u64 v[168:169], s[50:51], 0, v[164:165]
	s_add_i32 m0, s38, 0xc000
	ds_read_b128 v[190:193], v172
	ds_read_b128 v[194:197], v172 offset:1024
	ds_read_b128 v[204:207], v172 offset:2048
	ds_read_b128 v[208:211], v172 offset:3072
	ds_read_b128 v[212:215], v172 offset:4096
	ds_read_b128 v[216:219], v172 offset:5120
	ds_read_b128 v[220:223], v172 offset:6144
	ds_read_b128 v[224:227], v172 offset:7168
	global_load_lds_dwordx4 v[168:169], off
	v_lshl_add_u64 v[168:169], s[50:51], 0, v[166:167]
	s_add_i32 m0, s38, 0xe000
	s_nop 0
	global_load_lds_dwordx4 v[168:169], off
	s_waitcnt vmcnt(8)
	s_waitcnt lgkmcnt(0)
	s_barrier
	s_setprio 1
	s_waitcnt lgkmcnt(0)
	v_mfma_f32_16x16x32_bf16 v[142:145], v[88:91], v[190:193], v[142:145]
	v_mfma_f32_16x16x32_bf16 v[138:141], v[104:107], v[190:193], v[138:141]
	v_mfma_f32_16x16x32_bf16 v[130:133], v[88:91], v[204:207], v[130:133]
	v_mfma_f32_16x16x32_bf16 v[120:123], v[104:107], v[204:207], v[120:123]
	v_mfma_f32_16x16x32_bf16 v[96:99], v[88:91], v[212:215], v[96:99]
	v_mfma_f32_16x16x32_bf16 v[92:95], v[104:107], v[212:215], v[92:95]
	v_mfma_f32_16x16x32_bf16 v[80:83], v[88:91], v[220:223], v[80:83]
	v_mfma_f32_16x16x32_bf16 v[72:75], v[104:107], v[220:223], v[72:75]
	v_mfma_f32_16x16x32_bf16 v[142:145], v[100:103], v[194:197], v[142:145]
	v_mfma_f32_16x16x32_bf16 v[138:141], v[108:111], v[194:197], v[138:141]
	v_mfma_f32_16x16x32_bf16 v[130:133], v[100:103], v[208:211], v[130:133]
	v_mfma_f32_16x16x32_bf16 v[120:123], v[108:111], v[208:211], v[120:123]
	v_mfma_f32_16x16x32_bf16 v[96:99], v[100:103], v[216:219], v[96:99]
	v_mfma_f32_16x16x32_bf16 v[92:95], v[108:111], v[216:219], v[92:95]
	v_mfma_f32_16x16x32_bf16 v[80:83], v[100:103], v[224:227], v[80:83]
	v_mfma_f32_16x16x32_bf16 v[72:75], v[108:111], v[224:227], v[72:75]
	s_setprio 0
	s_setprio 1
	v_mfma_f32_16x16x32_bf16 v[134:137], v[174:177], v[190:193], v[134:137]
	v_mfma_f32_16x16x32_bf16 v[124:127], v[182:185], v[190:193], v[124:127]
	v_mfma_f32_16x16x32_bf16 v[116:119], v[174:177], v[204:207], v[116:119]
	v_mfma_f32_16x16x32_bf16 v[112:115], v[182:185], v[204:207], v[112:115]
	v_mfma_f32_16x16x32_bf16 v[84:87], v[174:177], v[212:215], v[84:87]
	v_mfma_f32_16x16x32_bf16 v[76:79], v[182:185], v[212:215], v[76:79]
	v_mfma_f32_16x16x32_bf16 v[68:71], v[174:177], v[220:223], v[68:71]
	v_mfma_f32_16x16x32_bf16 v[64:67], v[182:185], v[220:223], v[64:67]
	v_mfma_f32_16x16x32_bf16 v[134:137], v[178:181], v[194:197], v[134:137]
	v_mfma_f32_16x16x32_bf16 v[124:127], v[186:189], v[194:197], v[124:127]
	v_mfma_f32_16x16x32_bf16 v[116:119], v[178:181], v[208:211], v[116:119]
	v_mfma_f32_16x16x32_bf16 v[112:115], v[186:189], v[208:211], v[112:115]
	v_mfma_f32_16x16x32_bf16 v[84:87], v[178:181], v[216:219], v[84:87]
	v_mfma_f32_16x16x32_bf16 v[76:79], v[186:189], v[216:219], v[76:79]
	v_mfma_f32_16x16x32_bf16 v[68:71], v[178:181], v[224:227], v[68:71]
	v_mfma_f32_16x16x32_bf16 v[64:67], v[186:189], v[224:227], v[64:67]
	s_setprio 0
	s_barrier
	s_add_i32 s20, s20, s25
	v_lshl_add_u64 v[168:169], s[58:59], 0, v[128:129]
	s_mov_b32 m0, s20
	ds_read_b128 v[190:193], v172 offset:16384
	ds_read_b128 v[194:197], v172 offset:17408
	ds_read_b128 v[204:207], v172 offset:18432
	ds_read_b128 v[208:211], v172 offset:19456
	ds_read_b128 v[212:215], v172 offset:20480
	ds_read_b128 v[216:219], v172 offset:21504
	ds_read_b128 v[220:223], v172 offset:22528
	ds_read_b128 v[224:227], v172 offset:23552
	global_load_lds_dwordx4 v[168:169], off
	s_add_i32 m0, s20, 0x2000
	s_add_u32 s50, s58, 0xb0000
	v_lshl_add_u64 v[198:199], s[58:59], 0, v[146:147]
	s_addc_u32 s51, s59, 0
	s_add_i32 s20, s35, s25
	global_load_lds_dwordx4 v[198:199], off
	v_lshl_add_u64 v[228:229], s[50:51], 0, v[128:129]
	s_mov_b32 m0, s20
	v_lshl_add_u64 v[230:231], vcc, 0, v[146:147]
	global_load_lds_dwordx4 v[228:229], off
	v_lshl_add_u64 v[228:229], s[50:51], 0, v[146:147]
	s_add_i32 m0, s20, 0x2000
	s_nop 0
	global_load_lds_dwordx4 v[228:229], off
	v_lshl_add_u64 v[228:229], vcc, 0, v[128:129]
	s_mov_b32 m0, s38
	s_nop 0
	global_load_lds_dwordx4 v[228:229], off
	s_mov_b32 m0, s18
	s_nop 0
	global_load_lds_dwordx4 v[230:231], off
	s_waitcnt vmcnt(8)
	s_waitcnt lgkmcnt(0)
	s_barrier
; #define PG8_STAGE(bufoff, gbase, voff) do { _Pragma("unroll") for (int _i = 0; _i < 2; ++_i) \
;         __builtin_amdgcn_global_load_lds((const unsigned*)((const char*)(gbase) + (voff)[_i]), (PG8_LAS unsigned*)(lds + (bufoff) + ldsw + _i * 8192), 16, 0, 0); } while (0)
; #define PG8_LDA(dst, b, h) do { _Pragma("unroll") for (int m = 0; m < 4; ++m) _Pragma("unroll") for (int k = 0; k < 2; ++k) dst[m][k] = *(const PG8_LAS bf16x8*)(lds + PG8_SA(b, h) + aoff + m * 2048 + k * 1024); } while (0)
; #define PG8_LDB(dst, b, h) do { _Pragma("unroll") for (int n = 0; n < 2; ++n) _Pragma("unroll") for (int k = 0; k < 2; ++k) dst[n][k] = *(const PG8_LAS bf16x8*)(lds + PG8_SB(b, h) + boff + n * 2048 + k * 1024); } while (0)
; #define PG8_MMA(ai, bj, At, Bt) do { __builtin_amdgcn_s_setprio(1); _Pragma("unroll") for (int m = 0; m < 4; ++m) _Pragma("unroll") for (int n = 0; n < 2; ++n) _Pragma("unroll") for (int k = 0; k < 2; ++k) \
;         acc[ai][bj][m][n] = __builtin_amdgcn_mfma_f32_16x16x32_bf16(Bt[n][k], At[m][k], acc[ai][bj][m][n], 0, 0, 0); __builtin_amdgcn_s_setprio(0); } while (0)
; #define PG8_WAIT_V(n) asm volatile("s_waitcnt vmcnt(" #n ")" ::: "memory")
; template <class Epi, class Sched, bool ALIGN_EPI = false, bool SP2 = false>
; __device__ __forceinline__ void gemm_phase(PG8_LAS unsigned char* lds, const Gemm g, const Sched& S, const Epi& E) {
;     ...
;             PG8_LDB(B0, 0, 0); PG8_LDB(B1, 0, 1); PG8_SCHED; PG8_LDA(At, 0, 0); PG8_STAGE(PG8_SA(1, 1), a1 + hstep, voffA);
;             PG8_WAIT_V(8); PG8_WAIT_L(0); PG8_BAR; PG8_MMA(0, 0, At, B0); PG8_MMA(0, 1, At, B1); PG8_BAR; PG8_SCHED;
;             PG8_LDA(At, 0, 1); PG8_STAGE(PG8_SB(0, 0), b2, voffB); PG8_STAGE(PG8_SB(0, 1), b2 + hstep, voffB); PG8_STAGE(PG8_SA(0, 0), a2, voffA);
;             PG8_WAIT_V(8); PG8_WAIT_L(0); PG8_BAR; PG8_MMA(1, 0, At, B0); PG8_MMA(1, 1, At, B1); PG8_BAR; PG8_SCHED;
;             PG8_LDB(B0, 1, 0); PG8_LDB(B1, 1, 1); PG8_SCHED; PG8_LDA(At, 1, 0); PG8_STAGE(PG8_SA(0, 1), a2 + hstep, voffA);
;             PG8_WAIT_V(8); PG8_WAIT_L(0); PG8_BAR; PG8_MMA(0, 0, At, B0); PG8_MMA(0, 1, At, B1); PG8_BAR; PG8_SCHED;
;             PG8_LDA(At, 1, 1); PG8_STAGE(PG8_SB(1, 0), b3, voffB); PG8_STAGE(PG8_SB(1, 1), b3 + hstep, voffB); PG8_STAGE(PG8_SA(1, 0), a3, voffA);
;             PG8_WAIT_V(8); PG8_WAIT_L(0); PG8_BAR; PG8_MMA(1, 0, At, B0); PG8_MMA(1, 1, At, B1); PG8_BAR; PG8_SCHED;
	s_setprio 1
	s_waitcnt lgkmcnt(0)
	v_mfma_f32_16x16x32_bf16 v[60:63], v[88:91], v[190:193], v[60:63]
	v_mfma_f32_16x16x32_bf16 v[56:59], v[104:107], v[190:193], v[56:59]
	v_mfma_f32_16x16x32_bf16 v[48:51], v[88:91], v[204:207], v[48:51]
	v_mfma_f32_16x16x32_bf16 v[40:43], v[104:107], v[204:207], v[40:43]
	v_mfma_f32_16x16x32_bf16 v[28:31], v[88:91], v[212:215], v[28:31]
	v_mfma_f32_16x16x32_bf16 v[24:27], v[104:107], v[212:215], v[24:27]
	v_mfma_f32_16x16x32_bf16 v[16:19], v[88:91], v[220:223], v[16:19]
	v_mfma_f32_16x16x32_bf16 v[8:11], v[104:107], v[220:223], v[8:11]
	v_mfma_f32_16x16x32_bf16 v[60:63], v[100:103], v[194:197], v[60:63]
	v_mfma_f32_16x16x32_bf16 v[56:59], v[108:111], v[194:197], v[56:59]
	v_mfma_f32_16x16x32_bf16 v[48:51], v[100:103], v[208:211], v[48:51]
	v_mfma_f32_16x16x32_bf16 v[40:43], v[108:111], v[208:211], v[40:43]
	v_mfma_f32_16x16x32_bf16 v[28:31], v[100:103], v[216:219], v[28:31]
	v_mfma_f32_16x16x32_bf16 v[24:27], v[108:111], v[216:219], v[24:27]
	v_mfma_f32_16x16x32_bf16 v[16:19], v[100:103], v[224:227], v[16:19]
	v_mfma_f32_16x16x32_bf16 v[8:11], v[108:111], v[224:227], v[8:11]
	s_setprio 0
	s_setprio 1
	v_mfma_f32_16x16x32_bf16 v[52:55], v[174:177], v[190:193], v[52:55]
	v_mfma_f32_16x16x32_bf16 v[44:47], v[182:185], v[190:193], v[44:47]
	v_mfma_f32_16x16x32_bf16 v[36:39], v[174:177], v[204:207], v[36:39]
	v_mfma_f32_16x16x32_bf16 v[32:35], v[182:185], v[204:207], v[32:35]
	v_mfma_f32_16x16x32_bf16 v[20:23], v[174:177], v[212:215], v[20:23]
	v_mfma_f32_16x16x32_bf16 v[12:15], v[182:185], v[212:215], v[12:15]
	v_mfma_f32_16x16x32_bf16 v[4:7], v[174:177], v[220:223], v[4:7]
	v_mfma_f32_16x16x32_bf16 v[0:3], v[182:185], v[220:223], v[0:3]
	v_mfma_f32_16x16x32_bf16 v[52:55], v[178:181], v[194:197], v[52:55]
	v_mfma_f32_16x16x32_bf16 v[44:47], v[186:189], v[194:197], v[44:47]
	v_mfma_f32_16x16x32_bf16 v[36:39], v[178:181], v[208:211], v[36:39]
	v_mfma_f32_16x16x32_bf16 v[32:35], v[186:189], v[208:211], v[32:35]
	v_mfma_f32_16x16x32_bf16 v[20:23], v[178:181], v[216:219], v[20:23]
	v_mfma_f32_16x16x32_bf16 v[12:15], v[186:189], v[216:219], v[12:15]
	v_mfma_f32_16x16x32_bf16 v[4:7], v[178:181], v[224:227], v[4:7]
	v_mfma_f32_16x16x32_bf16 v[0:3], v[186:189], v[224:227], v[0:3]
	s_setprio 0
	s_barrier
	s_add_i32 s20, 0, 0x18000
	s_add_i32 s35, 0, 0x1c000
	v_add_u32_e32 v108, s20, v170
	v_add_u32_e32 v173, s35, v170
	ds_read_b128 v[88:91], v108
	ds_read_b128 v[100:103], v108 offset:1024
	ds_read_b128 v[104:107], v108 offset:2048
	ds_read_b128 v[108:111], v108 offset:3072
	ds_read_b128 v[174:177], v173
	ds_read_b128 v[178:181], v173 offset:1024
	ds_read_b128 v[182:185], v173 offset:2048
	ds_read_b128 v[186:189], v173 offset:3072
	s_add_u32 s50, vcc_lo, 0xb0000
	s_addc_u32 s51, vcc_hi, 0
	s_mov_b32 m0, s19
	v_lshl_add_u64 v[232:233], s[50:51], 0, v[128:129]
	ds_read_b128 v[190:193], v172 offset:32768
	ds_read_b128 v[194:197], v172 offset:33792
	ds_read_b128 v[204:207], v172 offset:34816
	ds_read_b128 v[208:211], v172 offset:35840
	ds_read_b128 v[212:215], v172 offset:36864
	ds_read_b128 v[216:219], v172 offset:37888
	ds_read_b128 v[220:223], v172 offset:38912
	ds_read_b128 v[224:227], v172 offset:39936
	global_load_lds_dwordx4 v[232:233], off
	v_lshl_add_u64 v[232:233], s[50:51], 0, v[146:147]
	s_mov_b32 m0, s39
	s_nop 0
	global_load_lds_dwordx4 v[232:233], off
	s_waitcnt vmcnt(8)
	s_waitcnt lgkmcnt(0)
	s_barrier
	s_setprio 1
	s_waitcnt lgkmcnt(0)
	v_mfma_f32_16x16x32_bf16 v[142:145], v[88:91], v[190:193], v[142:145]
	v_mfma_f32_16x16x32_bf16 v[138:141], v[104:107], v[190:193], v[138:141]
	v_mfma_f32_16x16x32_bf16 v[130:133], v[88:91], v[204:207], v[130:133]
	v_mfma_f32_16x16x32_bf16 v[120:123], v[104:107], v[204:207], v[120:123]
	v_mfma_f32_16x16x32_bf16 v[96:99], v[88:91], v[212:215], v[96:99]
	v_mfma_f32_16x16x32_bf16 v[92:95], v[104:107], v[212:215], v[92:95]
	v_mfma_f32_16x16x32_bf16 v[80:83], v[88:91], v[220:223], v[80:83]
	v_mfma_f32_16x16x32_bf16 v[72:75], v[104:107], v[220:223], v[72:75]
	v_mfma_f32_16x16x32_bf16 v[142:145], v[100:103], v[194:197], v[142:145]
	v_mfma_f32_16x16x32_bf16 v[138:141], v[108:111], v[194:197], v[138:141]
	v_mfma_f32_16x16x32_bf16 v[130:133], v[100:103], v[208:211], v[130:133]
	v_mfma_f32_16x16x32_bf16 v[120:123], v[108:111], v[208:211], v[120:123]
	v_mfma_f32_16x16x32_bf16 v[96:99], v[100:103], v[216:219], v[96:99]
	v_mfma_f32_16x16x32_bf16 v[92:95], v[108:111], v[216:219], v[92:95]
	v_mfma_f32_16x16x32_bf16 v[80:83], v[100:103], v[224:227], v[80:83]
	v_mfma_f32_16x16x32_bf16 v[72:75], v[108:111], v[224:227], v[72:75]
	s_setprio 0
	s_setprio 1
	v_mfma_f32_16x16x32_bf16 v[134:137], v[174:177], v[190:193], v[134:137]
	v_mfma_f32_16x16x32_bf16 v[124:127], v[182:185], v[190:193], v[124:127]
	v_mfma_f32_16x16x32_bf16 v[116:119], v[174:177], v[204:207], v[116:119]
	v_mfma_f32_16x16x32_bf16 v[112:115], v[182:185], v[204:207], v[112:115]
	v_mfma_f32_16x16x32_bf16 v[84:87], v[174:177], v[212:215], v[84:87]
	v_mfma_f32_16x16x32_bf16 v[76:79], v[182:185], v[212:215], v[76:79]
	v_mfma_f32_16x16x32_bf16 v[68:71], v[174:177], v[220:223], v[68:71]
	v_mfma_f32_16x16x32_bf16 v[64:67], v[182:185], v[220:223], v[64:67]
	v_mfma_f32_16x16x32_bf16 v[134:137], v[178:181], v[194:197], v[134:137]
	v_mfma_f32_16x16x32_bf16 v[124:127], v[186:189], v[194:197], v[124:127]
	v_mfma_f32_16x16x32_bf16 v[116:119], v[178:181], v[208:211], v[116:119]
	v_mfma_f32_16x16x32_bf16 v[112:115], v[186:189], v[208:211], v[112:115]
	v_mfma_f32_16x16x32_bf16 v[84:87], v[178:181], v[216:219], v[84:87]
	v_mfma_f32_16x16x32_bf16 v[76:79], v[186:189], v[216:219], v[76:79]
	v_mfma_f32_16x16x32_bf16 v[68:71], v[178:181], v[224:227], v[68:71]
	v_mfma_f32_16x16x32_bf16 v[64:67], v[186:189], v[224:227], v[64:67]
	s_setprio 0
	s_barrier
; #define PG8_STAGE(bufoff, gbase, voff) do { _Pragma("unroll") for (int _i = 0; _i < 2; ++_i) \
;         __builtin_amdgcn_global_load_lds((const unsigned*)((const char*)(gbase) + (voff)[_i]), (PG8_LAS unsigned*)(lds + (bufoff) + ldsw + _i * 8192), 16, 0, 0); } while (0)
; #define PG8_LDA(dst, b, h) do { _Pragma("unroll") for (int m = 0; m < 4; ++m) _Pragma("unroll") for (int k = 0; k < 2; ++k) dst[m][k] = *(const PG8_LAS bf16x8*)(lds + PG8_SA(b, h) + aoff + m * 2048 + k * 1024); } while (0)
; #define PG8_MMA(ai, bj, At, Bt) do { __builtin_amdgcn_s_setprio(1); _Pragma("unroll") for (int m = 0; m < 4; ++m) _Pragma("unroll") for (int n = 0; n < 2; ++n) _Pragma("unroll") for (int k = 0; k < 2; ++k) \
;         acc[ai][bj][m][n] = __builtin_amdgcn_mfma_f32_16x16x32_bf16(Bt[n][k], At[m][k], acc[ai][bj][m][n], 0, 0, 0); __builtin_amdgcn_s_setprio(0); } while (0)
; #define PG8_WAIT_V(n) asm volatile("s_waitcnt vmcnt(" #n ")" ::: "memory")
; #define PG8_WAIT_L(n) asm volatile("s_waitcnt lgkmcnt(" #n ")" ::: "memory")
; #define PG8_BAR __builtin_amdgcn_s_barrier()
; #define PG8_SCHED __builtin_amdgcn_sched_barrier(0)
; template <class Epi, class Sched, bool ALIGN_EPI = false, bool SP2 = false>
; __device__ __forceinline__ void gemm_phase(PG8_LAS unsigned char* lds, const Gemm g, const Sched& S, const Epi& E) {
;     ...
;             PG8_WAIT_V(8); PG8_WAIT_L(0); PG8_BAR; PG8_MMA(0, 0, At, B0); PG8_MMA(0, 1, At, B1); PG8_BAR; PG8_SCHED;
;             PG8_LDA(At, 1, 1); PG8_STAGE(PG8_SB(1, 0), b3, voffB); PG8_STAGE(PG8_SB(1, 1), b3 + hstep, voffB); PG8_STAGE(PG8_SA(1, 0), a3, voffA);
;             PG8_WAIT_V(8); PG8_WAIT_L(0); PG8_BAR; PG8_MMA(1, 0, At, B0); PG8_MMA(1, 1, At, B1); PG8_BAR; PG8_SCHED;
;     ...
;         if constexpr (ALIGN_EPI) { if (wr == 0) PG8_BAR; }
;         if constexpr (!Epi::AFTER_DRAIN) { E(acc, cur, wr, wc, fr, fq); S.done(cur); }
	s_add_i32 s20, s20, s25
	v_lshl_add_u64 v[168:169], v[168:169], 0, s[30:31]
	s_mov_b32 m0, s20
	ds_read_b128 v[190:193], v172 offset:49152
	ds_read_b128 v[194:197], v172 offset:50176
	ds_read_b128 v[204:207], v172 offset:51200
	ds_read_b128 v[208:211], v172 offset:52224
	ds_read_b128 v[212:215], v172 offset:53248
	ds_read_b128 v[216:219], v172 offset:54272
	ds_read_b128 v[220:223], v172 offset:55296
	ds_read_b128 v[224:227], v172 offset:56320
	global_load_lds_dwordx4 v[168:169], off
	s_add_i32 m0, s20, 0x2000
	s_add_u32 s50, s58, 0xb0080
	v_lshl_add_u64 v[168:169], v[198:199], 0, s[30:31]
	s_addc_u32 s51, s59, 0
	s_add_i32 s20, s35, s25
	global_load_lds_dwordx4 v[168:169], off
	v_lshl_add_u64 v[168:169], s[50:51], 0, v[128:129]
	s_mov_b32 m0, s20
	s_nop 0
	global_load_lds_dwordx4 v[168:169], off
	v_lshl_add_u64 v[168:169], s[50:51], 0, v[146:147]
	s_add_i32 m0, s20, 0x2000
	s_nop 0
	global_load_lds_dwordx4 v[168:169], off
	v_lshl_add_u64 v[168:169], v[228:229], 0, s[30:31]
	s_mov_b32 m0, s44
	s_nop 0
	global_load_lds_dwordx4 v[168:169], off
	v_lshl_add_u64 v[168:169], v[230:231], 0, s[30:31]
	s_mov_b32 m0, s45
	s_nop 0
	global_load_lds_dwordx4 v[168:169], off
	s_waitcnt vmcnt(8)
	s_waitcnt lgkmcnt(0)
	s_barrier
	s_setprio 1
	s_waitcnt lgkmcnt(0)
	v_mfma_f32_16x16x32_bf16 v[60:63], v[88:91], v[190:193], v[60:63]
	v_mfma_f32_16x16x32_bf16 v[56:59], v[104:107], v[190:193], v[56:59]
	v_mfma_f32_16x16x32_bf16 v[48:51], v[88:91], v[204:207], v[48:51]
	v_mfma_f32_16x16x32_bf16 v[40:43], v[104:107], v[204:207], v[40:43]
	v_mfma_f32_16x16x32_bf16 v[28:31], v[88:91], v[212:215], v[28:31]
	v_mfma_f32_16x16x32_bf16 v[24:27], v[104:107], v[212:215], v[24:27]
	v_mfma_f32_16x16x32_bf16 v[16:19], v[88:91], v[220:223], v[16:19]
	v_mfma_f32_16x16x32_bf16 v[8:11], v[104:107], v[220:223], v[8:11]
	v_mfma_f32_16x16x32_bf16 v[60:63], v[100:103], v[194:197], v[60:63]
	v_mfma_f32_16x16x32_bf16 v[56:59], v[108:111], v[194:197], v[56:59]
	v_mfma_f32_16x16x32_bf16 v[48:51], v[100:103], v[208:211], v[48:51]
	v_mfma_f32_16x16x32_bf16 v[40:43], v[108:111], v[208:211], v[40:43]
	v_mfma_f32_16x16x32_bf16 v[28:31], v[100:103], v[216:219], v[28:31]
	v_mfma_f32_16x16x32_bf16 v[24:27], v[108:111], v[216:219], v[24:27]
	v_mfma_f32_16x16x32_bf16 v[16:19], v[100:103], v[224:227], v[16:19]
	v_mfma_f32_16x16x32_bf16 v[8:11], v[108:111], v[224:227], v[8:11]
	s_setprio 0
	s_setprio 1
	v_mfma_f32_16x16x32_bf16 v[52:55], v[174:177], v[190:193], v[52:55]
	v_mfma_f32_16x16x32_bf16 v[44:47], v[182:185], v[190:193], v[44:47]
	v_mfma_f32_16x16x32_bf16 v[36:39], v[174:177], v[204:207], v[36:39]
	v_mfma_f32_16x16x32_bf16 v[32:35], v[182:185], v[204:207], v[32:35]
	v_mfma_f32_16x16x32_bf16 v[20:23], v[174:177], v[212:215], v[20:23]
	v_mfma_f32_16x16x32_bf16 v[12:15], v[182:185], v[212:215], v[12:15]
	v_mfma_f32_16x16x32_bf16 v[4:7], v[174:177], v[220:223], v[4:7]
	v_mfma_f32_16x16x32_bf16 v[0:3], v[182:185], v[220:223], v[0:3]
	v_mfma_f32_16x16x32_bf16 v[52:55], v[178:181], v[194:197], v[52:55]
	v_mfma_f32_16x16x32_bf16 v[44:47], v[186:189], v[194:197], v[44:47]
	v_mfma_f32_16x16x32_bf16 v[36:39], v[178:181], v[208:211], v[36:39]
	v_mfma_f32_16x16x32_bf16 v[32:35], v[186:189], v[208:211], v[32:35]
	v_mfma_f32_16x16x32_bf16 v[20:23], v[178:181], v[216:219], v[20:23]
	v_mfma_f32_16x16x32_bf16 v[12:15], v[186:189], v[216:219], v[12:15]
	v_mfma_f32_16x16x32_bf16 v[4:7], v[178:181], v[224:227], v[4:7]
	v_mfma_f32_16x16x32_bf16 v[0:3], v[186:189], v[224:227], v[0:3]
	s_setprio 0
	s_barrier
	s_add_i32 s34, s34, 2
	s_add_u32 s12, s12, 0x100
	s_addc_u32 s13, s13, 0
	s_cmp_gt_u32 s34, s101
	s_mov_b64 s[50:51], s[56:57]
	s_cbranch_scc0 .LBB0_1093
	s_and_b64 vcc, exec, s[36:37]
	s_cbranch_vccz .LBB0_1096
	s_barrier
.LBB0_1096:
	s_cmp_lg_u32 s15, 3
	s_cbranch_scc1 .Lks4_w
	s_cmp_lg_u32 s60, 0x100
	s_cbranch_scc1 .Lks4_w
	s_cmp_lt_u32 s2, 64
	s_cbranch_scc1 .Lks4_w
	s_cmp_gt_u32 s2, 127
	s_cbranch_scc1 .Lks4_w
	v_readlane_b32 s12, v254, 55
	v_readlane_b32 s13, v254, 56
	v_readlane_b32 s20, v255, 0
	s_nop 3
	s_load_dwordx2 s[12:13], s[12:13], 0xa0
	s_add_u32 s20, s20, 1
	s_sub_u32 s34, s2, 64
	s_lshl_b32 s34, s34, 2
	s_mov_b32 s35, 0
	s_waitcnt lgkmcnt(0)
	s_add_u32 s34, s34, 0x4204
	s_add_u32 s12, s12, s34
	s_addc_u32 s13, s13, 0
.Lks4_spin:
	global_load_dword v108, v129, s[12:13] sc1
	s_waitcnt vmcnt(0)
	v_readfirstlane_b32 s34, v108
	s_nop 3
	s_cmp_ge_u32 s34, s20
	s_cbranch_scc1 .Lks4_go
	s_sleep 1
	s_add_u32 s35, s35, 1
	s_cmp_lt_u32 s35, 0x10000
	s_cbranch_scc1 .Lks4_spin
.Lks4_go:
	buffer_inv sc1
	s_waitcnt vmcnt(0)

;     __device__ __forceinline__ void operator()(const pg8::f32x4 (&acc)[2][2][4][2], const pg8::Unit& u, int wr, int wc, int fr, int fq) const {
;         const int b = u.pm / 9, j = u.pm - b * 9;
;         float* base = (j == 0) ? xc + (size_t)b * CTX * DM : out + ((size_t)b * SEQ + (size_t)(j - 1) * 256) * DM;
;         const float* g = gate + (size_t)((j == 0) ? 16 : b) * MODW;
;         const int col0 = u.pn * 256 + wc * 32 + 4 * fq;
;         pg8::f32x4 gv[2][2];
; #pragma unroll
;         for (int bj = 0; bj < 2; ++bj)
; #pragma unroll
;             for (int n = 0; n < 2; ++n) gv[bj][n] = *(const pg8::f32x4*)(g + col0 + bj * 128 + n * 16);
; #pragma unroll
;         for (int ai = 0; ai < 2; ++ai)
; #pragma unroll
;             for (int m = 0; m < 4; ++m) {
;                 float* rowp = base + (size_t)(ai * 128 + wr * 64 + m * 16 + fr) * DM + col0;
; #pragma unroll
;                 for (int bj = 0; bj < 2; ++bj)
; #pragma unroll
;                     for (int n = 0; n < 2; ++n) {
;                         pg8::f32x4* p = (pg8::f32x4*)(rowp + bj * 128 + n * 16);
;                         pg8::f32x4 xv = *p; xv = xv + gv[bj][n] * acc[ai][bj][m][n]; *p = xv;
;                     }
;                 if (m & 1) asm volatile("" ::: "memory");
;             }
.LBB0_1099:
	s_lshl_b64 s[12:13], s[58:59], 2
	v_lshl_or_b32 v88, s62, 8, v171
	s_add_u32 s12, s11, s12
	v_ashrrev_i32_e32 v89, 31, v88
	s_addc_u32 s13, s24, s13
	v_lshlrev_b64 v[168:169], 2, v[88:89]
	v_lshl_add_u64 v[88:89], s[12:13], 0, v[168:169]
	v_lshl_add_u64 v[168:169], s[50:51], 0, v[168:169]
	v_lshl_add_u64 v[178:179], v[168:169], 0, v[148:149]
	global_load_dwordx4 v[108:111], v[88:89], off
	global_load_dwordx4 v[104:107], v[88:89], off offset:64
	global_load_dwordx4 v[100:103], v[88:89], off offset:512
	s_nop 0
	global_load_dwordx4 v[88:91], v[88:89], off offset:576
	s_mov_b64 s[50:51], -1
	global_load_dwordx4 v[174:177], v[178:179], off
	s_and_b64 vcc, exec, s[40:41]
	s_waitcnt vmcnt(0)
	v_pk_fma_f32 v[144:145], v[144:145], v[110:111], v[176:177]
	v_pk_fma_f32 v[142:143], v[142:143], v[108:109], v[174:175]
	global_store_dwordx4 v[178:179], v[142:145], off
	global_load_dwordx4 v[142:145], v[178:179], off offset:64
	s_waitcnt vmcnt(0)
	v_pk_fma_f32 v[140:141], v[140:141], v[106:107], v[144:145]
	v_pk_fma_f32 v[138:139], v[138:139], v[104:105], v[142:143]
	global_store_dwordx4 v[178:179], v[138:141], off offset:64
	global_load_dwordx4 v[138:141], v[178:179], off offset:512
	s_waitcnt vmcnt(0)
	v_pk_fma_f32 v[136:137], v[136:137], v[102:103], v[140:141]
	v_pk_fma_f32 v[134:135], v[134:135], v[100:101], v[138:139]
	global_store_dwordx4 v[178:179], v[134:137], off offset:512
	global_load_dwordx4 v[134:137], v[178:179], off offset:576
	s_waitcnt vmcnt(0)
	v_pk_fma_f32 v[126:127], v[126:127], v[90:91], v[136:137]
	v_pk_fma_f32 v[124:125], v[124:125], v[88:89], v[134:135]
	v_lshl_add_u64 v[134:135], v[168:169], 0, v[150:151]
	global_store_dwordx4 v[178:179], v[124:127], off offset:576
	global_load_dwordx4 v[124:127], v[134:135], off
	s_waitcnt vmcnt(0)
	v_pk_fma_f32 v[126:127], v[132:133], v[110:111], v[126:127]
	v_pk_fma_f32 v[124:125], v[130:131], v[108:109], v[124:125]
	global_store_dwordx4 v[134:135], v[124:127], off
	global_load_dwordx4 v[124:127], v[134:135], off offset:64
	s_waitcnt vmcnt(0)
	v_pk_fma_f32 v[122:123], v[122:123], v[106:107], v[126:127]
	v_pk_fma_f32 v[120:121], v[120:121], v[104:105], v[124:125]
	global_store_dwordx4 v[134:135], v[120:123], off offset:64
	global_load_dwordx4 v[120:123], v[134:135], off offset:512
	s_waitcnt vmcnt(0)
	v_pk_fma_f32 v[118:119], v[118:119], v[102:103], v[122:123]
	v_pk_fma_f32 v[116:117], v[116:117], v[100:101], v[120:121]
	global_store_dwordx4 v[134:135], v[116:119], off offset:512
	global_load_dwordx4 v[116:119], v[134:135], off offset:576
	s_waitcnt vmcnt(0)
	v_pk_fma_f32 v[114:115], v[114:115], v[90:91], v[118:119]
	v_pk_fma_f32 v[112:113], v[112:113], v[88:89], v[116:117]
	global_store_dwordx4 v[134:135], v[112:115], off offset:576
	v_lshl_add_u64 v[116:117], v[168:169], 0, v[152:153]
	global_load_dwordx4 v[112:115], v[116:117], off
	s_waitcnt vmcnt(0)
	v_pk_fma_f32 v[98:99], v[98:99], v[110:111], v[114:115]
	v_pk_fma_f32 v[96:97], v[96:97], v[108:109], v[112:113]
	global_store_dwordx4 v[116:117], v[96:99], off
	global_load_dwordx4 v[96:99], v[116:117], off offset:64
	s_waitcnt vmcnt(0)
	v_pk_fma_f32 v[94:95], v[94:95], v[106:107], v[98:99]
	v_pk_fma_f32 v[92:93], v[92:93], v[104:105], v[96:97]
	global_store_dwordx4 v[116:117], v[92:95], off offset:64
	global_load_dwordx4 v[92:95], v[116:117], off offset:512
	s_waitcnt vmcnt(0)
	v_pk_fma_f32 v[86:87], v[86:87], v[102:103], v[94:95]
	v_pk_fma_f32 v[84:85], v[84:85], v[100:101], v[92:93]
	global_store_dwordx4 v[116:117], v[84:87], off offset:512
	global_load_dwordx4 v[84:87], v[116:117], off offset:576
	s_waitcnt vmcnt(0)
	v_pk_fma_f32 v[78:79], v[78:79], v[90:91], v[86:87]
	v_pk_fma_f32 v[76:77], v[76:77], v[88:89], v[84:85]
	v_lshl_add_u64 v[84:85], v[168:169], 0, v[154:155]
	global_store_dwordx4 v[116:117], v[76:79], off offset:576
	global_load_dwordx4 v[76:79], v[84:85], off
	s_waitcnt vmcnt(0)
	v_pk_fma_f32 v[78:79], v[82:83], v[110:111], v[78:79]
	v_pk_fma_f32 v[76:77], v[80:81], v[108:109], v[76:77]
	global_store_dwordx4 v[84:85], v[76:79], off
	global_load_dwordx4 v[76:79], v[84:85], off offset:64
	s_waitcnt vmcnt(0)
	v_pk_fma_f32 v[74:75], v[74:75], v[106:107], v[78:79]
	v_pk_fma_f32 v[72:73], v[72:73], v[104:105], v[76:77]
	global_store_dwordx4 v[84:85], v[72:75], off offset:64
	global_load_dwordx4 v[72:75], v[84:85], off offset:512
	s_waitcnt vmcnt(0)
	v_pk_fma_f32 v[70:71], v[70:71], v[102:103], v[74:75]
	v_pk_fma_f32 v[68:69], v[68:69], v[100:101], v[72:73]
	global_store_dwordx4 v[84:85], v[68:71], off offset:512
	global_load_dwordx4 v[68:71], v[84:85], off offset:576
	s_waitcnt vmcnt(0)
	v_pk_fma_f32 v[66:67], v[66:67], v[90:91], v[70:71]
	v_pk_fma_f32 v[64:65], v[64:65], v[88:89], v[68:69]
	global_store_dwordx4 v[84:85], v[64:67], off offset:576
	v_lshl_add_u64 v[68:69], v[168:169], 0, v[156:157]
	global_load_dwordx4 v[64:67], v[68:69], off
	s_waitcnt vmcnt(0)
;     __device__ __forceinline__ void operator()(const pg8::f32x4 (&acc)[2][2][4][2], const pg8::Unit& u, int wr, int wc, int fr, int fq) const {
;     ...
;         for (int ai = 0; ai < 2; ++ai)
; #pragma unroll
;             for (int m = 0; m < 4; ++m) {
;                 float* rowp = base + (size_t)(ai * 128 + wr * 64 + m * 16 + fr) * DM + col0;
; #pragma unroll
;                 for (int bj = 0; bj < 2; ++bj)
; #pragma unroll
;                     for (int n = 0; n < 2; ++n) {
;                         pg8::f32x4* p = (pg8::f32x4*)(rowp + bj * 128 + n * 16);
;                         pg8::f32x4 xv = *p; xv = xv + gv[bj][n] * acc[ai][bj][m][n]; *p = xv;
;                     }
;                 if (m & 1) asm volatile("" ::: "memory");
;             }
	v_pk_fma_f32 v[62:63], v[62:63], v[110:111], v[66:67]
	v_pk_fma_f32 v[60:61], v[60:61], v[108:109], v[64:65]
	global_store_dwordx4 v[68:69], v[60:63], off
	global_load_dwordx4 v[60:63], v[68:69], off offset:64
	s_waitcnt vmcnt(0)
	v_pk_fma_f32 v[58:59], v[58:59], v[106:107], v[62:63]
	v_pk_fma_f32 v[56:57], v[56:57], v[104:105], v[60:61]
	global_store_dwordx4 v[68:69], v[56:59], off offset:64
	global_load_dwordx4 v[56:59], v[68:69], off offset:512
	s_waitcnt vmcnt(0)
	v_pk_fma_f32 v[54:55], v[54:55], v[102:103], v[58:59]
	v_pk_fma_f32 v[52:53], v[52:53], v[100:101], v[56:57]
	global_store_dwordx4 v[68:69], v[52:55], off offset:512
	global_load_dwordx4 v[52:55], v[68:69], off offset:576
	s_waitcnt vmcnt(0)
	v_pk_fma_f32 v[46:47], v[46:47], v[90:91], v[54:55]
	v_pk_fma_f32 v[44:45], v[44:45], v[88:89], v[52:53]
	v_lshl_add_u64 v[52:53], v[168:169], 0, v[158:159]
	global_store_dwordx4 v[68:69], v[44:47], off offset:576
	global_load_dwordx4 v[44:47], v[52:53], off
	s_waitcnt vmcnt(0)
	v_pk_fma_f32 v[46:47], v[50:51], v[110:111], v[46:47]
	v_pk_fma_f32 v[44:45], v[48:49], v[108:109], v[44:45]
	global_store_dwordx4 v[52:53], v[44:47], off
	global_load_dwordx4 v[44:47], v[52:53], off offset:64
	s_waitcnt vmcnt(0)
	v_pk_fma_f32 v[42:43], v[42:43], v[106:107], v[46:47]
	v_pk_fma_f32 v[40:41], v[40:41], v[104:105], v[44:45]
	global_store_dwordx4 v[52:53], v[40:43], off offset:64
	global_load_dwordx4 v[40:43], v[52:53], off offset:512
	s_waitcnt vmcnt(0)
	v_pk_fma_f32 v[38:39], v[38:39], v[102:103], v[42:43]
	v_pk_fma_f32 v[36:37], v[36:37], v[100:101], v[40:41]
	global_store_dwordx4 v[52:53], v[36:39], off offset:512
	global_load_dwordx4 v[36:39], v[52:53], off offset:576
	s_waitcnt vmcnt(0)
	v_pk_fma_f32 v[34:35], v[34:35], v[90:91], v[38:39]
	v_pk_fma_f32 v[32:33], v[32:33], v[88:89], v[36:37]
	global_store_dwordx4 v[52:53], v[32:35], off offset:576
	v_lshl_add_u64 v[36:37], v[168:169], 0, v[160:161]
	global_load_dwordx4 v[32:35], v[36:37], off
	s_waitcnt vmcnt(0)
	v_pk_fma_f32 v[30:31], v[30:31], v[110:111], v[34:35]
	v_pk_fma_f32 v[28:29], v[28:29], v[108:109], v[32:33]
	global_store_dwordx4 v[36:37], v[28:31], off
	global_load_dwordx4 v[28:31], v[36:37], off offset:64
	s_waitcnt vmcnt(0)
	v_pk_fma_f32 v[26:27], v[26:27], v[106:107], v[30:31]
	v_pk_fma_f32 v[24:25], v[24:25], v[104:105], v[28:29]
	global_store_dwordx4 v[36:37], v[24:27], off offset:64
	global_load_dwordx4 v[24:27], v[36:37], off offset:512
	s_waitcnt vmcnt(0)
	v_pk_fma_f32 v[22:23], v[22:23], v[102:103], v[26:27]
	v_pk_fma_f32 v[20:21], v[20:21], v[100:101], v[24:25]
	global_store_dwordx4 v[36:37], v[20:23], off offset:512
	global_load_dwordx4 v[20:23], v[36:37], off offset:576
	s_waitcnt vmcnt(0)
	v_pk_fma_f32 v[14:15], v[14:15], v[90:91], v[22:23]
	v_pk_fma_f32 v[12:13], v[12:13], v[88:89], v[20:21]
	v_lshl_add_u64 v[20:21], v[168:169], 0, v[162:163]
	global_store_dwordx4 v[36:37], v[12:15], off offset:576
	global_load_dwordx4 v[12:15], v[20:21], off
	s_waitcnt vmcnt(0)
	v_pk_fma_f32 v[14:15], v[18:19], v[110:111], v[14:15]
	v_pk_fma_f32 v[12:13], v[16:17], v[108:109], v[12:13]
	global_store_dwordx4 v[20:21], v[12:15], off
	global_load_dwordx4 v[12:15], v[20:21], off offset:64
	s_waitcnt vmcnt(0)
	v_pk_fma_f32 v[10:11], v[10:11], v[106:107], v[14:15]
	v_pk_fma_f32 v[8:9], v[8:9], v[104:105], v[12:13]
	global_store_dwordx4 v[20:21], v[8:11], off offset:64
	global_load_dwordx4 v[8:11], v[20:21], off offset:512
	s_waitcnt vmcnt(0)
	v_pk_fma_f32 v[6:7], v[6:7], v[102:103], v[10:11]
	v_pk_fma_f32 v[4:5], v[4:5], v[100:101], v[8:9]
	global_store_dwordx4 v[20:21], v[4:7], off offset:512
	global_load_dwordx4 v[4:7], v[20:21], off offset:576
	s_waitcnt vmcnt(0)
	v_pk_fma_f32 v[2:3], v[2:3], v[90:91], v[6:7]
	v_pk_fma_f32 v[0:1], v[0:1], v[88:89], v[4:5]
	global_store_dwordx4 v[20:21], v[0:3], off offset:576
	s_cmp_lg_u32 s15, 3
	s_cbranch_scc1 .Lks4_p
	s_cmp_lg_u32 s60, 0x100
	s_cbranch_scc1 .Lks4_p
	s_cmp_gt_u32 s2, 63
	s_cbranch_scc1 .Lks4_p
	s_waitcnt vmcnt(0)
	s_barrier
	v_readfirstlane_b32 s20, v200
	v_readlane_b32 s12, v254, 55
	v_readlane_b32 s13, v254, 56
	s_nop 3
	s_lshr_b32 s20, s20, 6
	s_cmp_lg_u32 s20, 0
	s_cbranch_scc1 .Lks4_p
	s_load_dwordx2 s[12:13], s[12:13], 0xa0
	buffer_wbl2 sc1
	v_mov_b32_e32 v0, 1
	s_lshl_b32 s20, s2, 2
	s_waitcnt vmcnt(0) lgkmcnt(0)
	s_add_u32 s20, s20, 0x4204
	s_add_u32 s12, s12, s20
	s_addc_u32 s13, s13, 0
	s_mov_b64 s[34:35], exec
	s_mov_b64 exec, 1
	global_atomic_add v129, v0, s[12:13]
	s_mov_b64 exec, s[34:35]
.Lks4_p:
	s_cbranch_vccnz .LBB0_1085
	s_andn2_b64 vcc, exec, s[0:1]
	s_cbranch_vccnz .LBB0_1084
	s_barrier
	s_branch .LBB0_1084
